# half of the workgroups (index bit 2) run the MLA up-projection GEMMs before the mLSTM scan, the others after
# speedup vs baseline: 1.0017x; 1.0017x over previous
; #define GRID_BAR(id_) do { XcdBarrier b2_ = bar; unsigned xx_ = bar.x; asm volatile("" : "+s"(xx_)); b2_.x = xx_; xcd_barrier(b2_); } while (0)
; #define LAUNDER() int tid = tid0; asm volatile("" : "+v"(tid)); int wg = blockIdx.x; asm volatile("" : "+s"(wg)); const int lane = tid & 63, wave = __builtin_amdgcn_readfirstlane(tid >> 6), gw = wg * NWAVES + wave, NGW = G * NWAVES; (void)lane; (void)wave; (void)gw; (void)NGW
; __device__ __forceinline__ void mlstm_scan(bf16* DC, float* DN, float* SC, int wg, int G, int tid) {
;     for (int unit = wg; unit < 32 * 8; unit += G) {
; __global__ void __launch_bounds__(NTHR, 2) fwd_kernel(Args a) {
;     ...
;         GRID_BAR(3);
;         { LAUNDER(); mlstm_scan(DC, DN, SC, wg, G, tid); }
.LBB0_652:
	s_or_b64 exec, exec, s[2:3]
	s_waitcnt lgkmcnt(0)
	s_barrier
	s_mov_b32 s100, 0
	s_bitcmp1_b32 s48, 2
	s_cbranch_scc0 .Lscan_late_entry
	s_mov_b32 s100, 1
	s_branch .LBB0_729
.Lscan_late_entry:
	v_mov_b32_e32 v2, v0
	s_mov_b32 s12, s48
	s_cmpk_gt_i32 s12, 0xff
	s_cbranch_scc1 .Lscan_exit
	v_ashrrev_i32_e32 v3, 31, v2
	v_and_b32_e32 v1, 63, v2
	v_cmp_gt_i32_e64 s[2:3], 64, v2
	v_lshlrev_b32_e32 v4, 2, v1
	v_lshlrev_b64 v[6:7], 2, v[2:3]
	s_mov_b32 s13, s12
	s_branch .LBB0_655

; __global__ void __launch_bounds__(NTHR, 2) fwd_kernel(Args a) {
;     ...
;         __syncthreads();
.Lscan_exit:
	s_cmp_eq_u32 s100, 2
	s_cbranch_scc1 .Lbar4_go

; #define GRID_BAR(id_) do { XcdBarrier b2_ = bar; unsigned xx_ = bar.x; asm volatile("" : "+s"(xx_)); b2_.x = xx_; xcd_barrier(b2_); } while (0)
; __global__ void __launch_bounds__(NTHR, 2) fwd_kernel(Args a) {
;     ...
;           pg8::gemm_phase<pg8::EpiBf16<0, false, true, 256, false>, pg8::StaticOrder, true, true, DINP>(L, g, S, E); }
;         GRID_BAR(4);
.LBB0_773:
	s_cmp_lg_u32 s100, 1
	s_cbranch_scc1 .Lbar4_go
	s_mov_b32 s100, 2
	s_branch .Lscan_late_entry
